# v35 + non-temporal loads of the residual rows in the final LayerNorm (last use)
# baseline (speedup 1.0000x reference)
; #define GASP __attribute__((address_space(1)))
; __device__ __forceinline__ void phase_ln(const bf16_t* src, float* dstf, bf16_t* dstb, const float* gam, const float* bet) {
;     const int lane = threadIdx.x & 63, gw = blockIdx.x * 8 + (threadIdx.x >> 6), NGW = gridDim.x * 8;
;     f32x4 gg[4], bb[4];
; #pragma unroll
;     for (int j = 0; j < 4; ++j) { gg[j] = ((const GASP f32x4*)gam)[64 * j + lane]; bb[j] = ((const GASP f32x4*)bet)[64 * j + lane]; }
;     for (int row = gw; row < M; row += NGW) {
;         const GASP u32x2* xr = (const GASP u32x2*)(src + (size_t)row * D) + lane;
;         u32x2 raw[4];
; #pragma unroll
;         for (int j = 0; j < 4; ++j) raw[j] = xr[64 * j];
.LBB0_1767:
	s_cmp_lt_i32 s54, 15
	s_cselect_b64 s[0:1], -1, 0
	s_cmp_gt_i32 s55, 14
	s_cselect_b64 s[4:5], -1, 0
	s_and_b64 s[0:1], s[0:1], s[4:5]
	s_andn2_b64 vcc, exec, s[0:1]
	s_cbranch_vccnz .LBB0_1771
	s_waitcnt vmcnt(0)
	v_lshl_add_u32 v32, s2, 3, v209
	s_mov_b32 s0, 0x8400
	v_cmp_gt_i32_e32 vcc, s0, v32
	s_and_saveexec_b64 s[0:1], vcc
	s_cbranch_execz .LBB0_1771
	v_readlane_b32 s4, v252, 1
	v_readlane_b32 s5, v252, 2
	s_load_dwordx4 s[0:3], s[4:5], 0x100
	s_load_dwordx2 s[6:7], s[4:5], 0x110
	v_and_b32_e32 v34, 63, v208
	v_lshlrev_b32_e32 v46, 4, v34
	v_mbcnt_lo_u32_b32 v33, -1, 0
	s_waitcnt lgkmcnt(0)
	global_load_dwordx4 v[0:3], v46, s[0:1]
	global_load_dwordx4 v[4:7], v46, s[2:3]
	global_load_dwordx4 v[8:11], v46, s[0:1] offset:1024
	global_load_dwordx4 v[12:15], v46, s[2:3] offset:1024
	global_load_dwordx4 v[16:19], v46, s[0:1] offset:2048
	global_load_dwordx4 v[20:23], v46, s[2:3] offset:2048
	global_load_dwordx4 v[24:27], v46, s[0:1] offset:3072
	global_load_dwordx4 v[28:31], v46, s[2:3] offset:3072
	v_mbcnt_hi_u32_b32 v33, -1, v33
	v_and_b32_e32 v36, 64, v33
	v_add_u32_e32 v36, 64, v36
	v_xor_b32_e32 v37, 1, v33
	v_cmp_lt_i32_e32 vcc, v37, v36
	s_lshl_b32 s2, s82, 3
	s_mov_b64 s[0:1], 0x3021000
	v_cndmask_b32_e32 v37, v33, v37, vcc
	v_lshlrev_b32_e32 v40, 2, v37
	v_xor_b32_e32 v37, 2, v33
	v_cmp_lt_i32_e32 vcc, v37, v36
	s_ashr_i32 s3, s2, 31
	v_mov_b32_e32 v35, 0
	v_cndmask_b32_e32 v37, v33, v37, vcc
	v_lshlrev_b32_e32 v41, 2, v37
	v_xor_b32_e32 v37, 4, v33
	v_cmp_lt_i32_e32 vcc, v37, v36
	s_lshl_b64 s[4:5], s[2:3], 11
	s_mov_b64 s[8:9], 0
	v_cndmask_b32_e32 v37, v33, v37, vcc
	v_lshlrev_b32_e32 v42, 2, v37
	v_xor_b32_e32 v37, 8, v33
	v_cmp_lt_i32_e32 vcc, v37, v36
	v_lshlrev_b32_e32 v34, 3, v34
	s_mov_b32 s10, 0x83ff
	v_cndmask_b32_e32 v37, v33, v37, vcc
	v_lshlrev_b32_e32 v43, 2, v37
	v_xor_b32_e32 v37, 16, v33
	v_cmp_lt_i32_e32 vcc, v37, v36
	s_nop 1
	v_cndmask_b32_e32 v37, v33, v37, vcc
	v_lshlrev_b32_e32 v44, 2, v37
	v_xor_b32_e32 v37, 32, v33
	v_cmp_lt_i32_e32 vcc, v37, v36
	s_nop 1
	v_cndmask_b32_e32 v33, v33, v37, vcc
	v_lshlrev_b32_e32 v45, 2, v33
	v_ashrrev_i32_e32 v33, 31, v32
	v_lshlrev_b64 v[36:37], 11, v[32:33]
	v_lshlrev_b64 v[38:39], 12, v[32:33]
	v_lshl_add_u64 v[36:37], s[52:53], 0, v[36:37]
	v_or_b32_e32 v38, v38, v46
	v_lshl_add_u64 v[36:37], v[36:37], 0, s[0:1]
	v_lshl_add_u64 v[38:39], s[6:7], 0, v[38:39]
	s_mov_b64 s[0:1], 0xc00
	v_lshl_add_u64 v[38:39], v[38:39], 0, s[0:1]
	s_lshl_b64 s[6:7], s[2:3], 12
	v_mov_b32_e32 v33, 0x3727c5ac
	s_mov_b32 s3, 0xf800000
	v_mov_b32_e32 v46, 0x260
	v_lshl_add_u64 v[48:49], v[36:37], 0, v[34:35]
	global_load_dwordx2 v[50:51], v[48:49], off nt
	global_load_dwordx2 v[52:53], v[48:49], off offset:512 nt
	global_load_dwordx2 v[54:55], v[48:49], off offset:1024 nt
	global_load_dwordx2 v[56:57], v[48:49], off offset:1536 nt
; #define GASP __attribute__((address_space(1)))
; __device__ __forceinline__ void phase_ln(const bf16_t* src, float* dstf, bf16_t* dstb, const float* gam, const float* bet) {
;     ...
;     for (int row = gw; row < M; row += NGW) {
;         const GASP u32x2* xr = (const GASP u32x2*)(src + (size_t)row * D) + lane;
;         u32x2 raw[4];
; #pragma unroll
;         for (int j = 0; j < 4; ++j) raw[j] = xr[64 * j];
;         f32x4 v[4]; float s = 0.f;
; #pragma unroll
;         for (int j = 0; j < 4; ++j) { v[j] = (f32x4){__uint_as_float(raw[j].x << 16), __uint_as_float(raw[j].x & 0xffff0000u), __uint_as_float(raw[j].y << 16), __uint_as_float(raw[j].y & 0xffff0000u)};
;             s += (v[j][0] + v[j][1]) + (v[j][2] + v[j][3]); }
;         const float mean = wave_sum(s) * (1.f / D); float s2 = 0.f;
; #pragma unroll
;         for (int j = 0; j < 4; ++j) { v[j] = v[j] - mean; s2 += (v[j][0] * v[j][0] + v[j][1] * v[j][1]) + (v[j][2] * v[j][2] + v[j][3] * v[j][3]); }
;         const float rstd = 1.f / sqrtf(wave_sum(s2) * (1.f / D) + LN_EPS);
; #pragma unroll
;         for (int j = 0; j < 4; ++j) {
;             const f32x4 y = v[j] * rstd * gg[j] + bb[j];
;             __builtin_nontemporal_store(y, (GASP f32x4*)(dstf + (size_t)row * D) + 64 * j + lane);
;             if (dstb) { u32x2 w; w.x = pk2(y[0], y[1]); w.y = pk2(y[2], y[3]); ((GASP u32x2*)(dstb + (size_t)row * D))[64 * j + lane] = w; }
;         }
;     }
.LBB0_1770:
	v_lshl_add_u64 v[36:37], v[36:37], 0, s[4:5]
	v_lshl_add_u64 v[48:49], v[36:37], 0, v[34:35]
	global_load_dwordx2 v[82:83], v[48:49], off nt
	global_load_dwordx2 v[84:85], v[48:49], off offset:512 nt
	global_load_dwordx2 v[86:87], v[48:49], off offset:1024 nt
	global_load_dwordx2 v[88:89], v[48:49], off offset:1536 nt
	v_add_u32_e32 v32, s2, v32
	v_cmp_lt_i32_e32 vcc, s10, v32
	s_or_b64 s[8:9], vcc, s[8:9]
	s_waitcnt vmcnt(4)
	v_lshlrev_b32_e32 v49, 16, v51
	v_lshlrev_b32_e32 v48, 16, v50
	v_and_b32_e32 v51, 0xffff0000, v51
	v_and_b32_e32 v50, 0xffff0000, v50
	v_lshlrev_b32_e32 v59, 16, v53
	v_lshlrev_b32_e32 v58, 16, v52
	v_and_b32_e32 v53, 0xffff0000, v53
	v_and_b32_e32 v52, 0xffff0000, v52
	v_pk_add_f32 v[68:69], v[48:49], v[50:51]
	v_pk_add_f32 v[70:71], v[58:59], v[52:53]
	v_lshlrev_b32_e32 v60, 16, v54
	v_and_b32_e32 v61, 0xffff0000, v54
	v_lshlrev_b32_e32 v54, 16, v55
	v_and_b32_e32 v55, 0xffff0000, v55
	v_and_b32_e32 v65, 0xffff0000, v56
	v_add_f32_e32 v47, v68, v69
	v_pk_add_f32 v[68:69], v[70:71], v[70:71] op_sel:[0,1] op_sel_hi:[1,0]
	v_lshlrev_b32_e32 v63, 16, v56
	v_lshlrev_b32_e32 v67, 16, v57
	v_and_b32_e32 v57, 0xffff0000, v57
	v_add_f32_e32 v66, v60, v61
	v_add_f32_e32 v56, v54, v55
	v_add_f32_e32 v62, 0, v47
	v_mov_b32_e32 v69, v65
	v_pk_add_f32 v[70:71], v[66:67], v[56:57]
	v_pk_add_f32 v[68:69], v[62:63], v[68:69]
	s_nop 0
	v_pk_add_f32 v[68:69], v[68:69], v[70:71]
	s_nop 0
	v_add_f32_e32 v47, v68, v69
	ds_bpermute_b32 v56, v40, v47
	s_waitcnt lgkmcnt(0)
	v_add_f32_e32 v47, v47, v56
	ds_bpermute_b32 v56, v41, v47
	s_waitcnt lgkmcnt(0)
	v_add_f32_e32 v47, v47, v56
	ds_bpermute_b32 v56, v42, v47
	s_waitcnt lgkmcnt(0)
	v_add_f32_e32 v47, v47, v56
	ds_bpermute_b32 v56, v43, v47
	s_waitcnt lgkmcnt(0)
	v_add_f32_e32 v47, v47, v56
	ds_bpermute_b32 v56, v44, v47
	s_waitcnt lgkmcnt(0)
	v_add_f32_e32 v47, v47, v56
	ds_bpermute_b32 v56, v45, v47
	s_waitcnt lgkmcnt(0)
	v_add_f32_e32 v47, v47, v56
	v_fmac_f32_e32 v50, 0xba800000, v47
	v_fmac_f32_e32 v51, 0xba800000, v47
	v_fmac_f32_e32 v49, 0xba800000, v47
	v_fmac_f32_e32 v52, 0xba800000, v47
	v_fmac_f32_e32 v53, 0xba800000, v47
	v_fmac_f32_e32 v59, 0xba800000, v47
	v_fmac_f32_e32 v48, 0xba800000, v47
	v_fmac_f32_e32 v58, 0xba800000, v47
	v_fmac_f32_e32 v60, 0xba800000, v47
	v_mov_b32_e32 v68, v49
	v_mov_b32_e32 v69, v51
	v_mov_b32_e32 v49, v50
	v_mov_b32_e32 v50, v59
	v_mov_b32_e32 v51, v53
	v_mov_b32_e32 v59, v52
	v_fmac_f32_e32 v61, 0xba800000, v47
	v_fmac_f32_e32 v54, 0xba800000, v47
	v_mul_f32_e32 v52, v60, v60
	v_pk_mul_f32 v[70:71], v[68:69], v[68:69]
	v_pk_mul_f32 v[72:73], v[48:49], v[48:49]
	v_pk_mul_f32 v[74:75], v[50:51], v[50:51]
	v_pk_mul_f32 v[76:77], v[58:59], v[58:59]
	v_fmac_f32_e32 v55, 0xba800000, v47
	v_fmac_f32_e32 v63, 0xba800000, v47
	v_mul_f32_e32 v62, v54, v54
	v_pk_fma_f32 v[52:53], v[60:61], v[60:61], v[52:53] op_sel_hi:[1,1,0]
	v_pk_mov_b32 v[80:81], v[72:73], v[70:71] op_sel:[1,0]
	v_mov_b32_e32 v73, v71
	v_pk_mov_b32 v[70:71], v[76:77], v[74:75] op_sel:[1,0]
	v_mov_b32_e32 v77, v75
	v_mov_b32_e32 v64, v63
	v_pk_fma_f32 v[78:79], v[54:55], v[54:55], v[62:63] op_sel_hi:[1,1,0]
	v_mul_f32_e32 v52, v63, v63
	v_pk_add_f32 v[62:63], v[80:81], v[72:73]
	v_pk_add_f32 v[70:71], v[70:71], v[76:77]
	v_fmac_f32_e32 v57, 0xba800000, v47
	v_fmac_f32_e32 v67, 0xba800000, v47
	v_fmac_f32_e32 v65, 0xba800000, v47
	v_pk_add_f32 v[62:63], v[62:63], v[62:63] op_sel_hi:[0,1]
	v_pk_add_f32 v[70:71], v[70:71], v[70:71] op_sel_hi:[0,1]
	v_mul_f32_e32 v78, v65, v65
	v_mul_f32_e32 v62, v67, v67
	v_mul_f32_e32 v70, v57, v57
	v_pk_add_f32 v[52:53], v[52:53], v[78:79]
	v_pk_add_f32 v[62:63], v[62:63], v[70:71]
	v_mov_b32_e32 v56, v67
	v_pk_add_f32 v[52:53], v[52:53], v[62:63]
	s_nop 0
	v_add_f32_e32 v47, v52, v53
	ds_bpermute_b32 v52, v40, v47
	s_waitcnt lgkmcnt(0)
	v_add_f32_e32 v47, v47, v52
	ds_bpermute_b32 v52, v41, v47
	s_waitcnt lgkmcnt(0)
	v_add_f32_e32 v47, v47, v52
	ds_bpermute_b32 v52, v42, v47
	s_waitcnt lgkmcnt(0)
	v_add_f32_e32 v47, v47, v52
	ds_bpermute_b32 v52, v43, v47
	s_waitcnt lgkmcnt(0)
	v_add_f32_e32 v47, v47, v52
	ds_bpermute_b32 v52, v44, v47
	s_waitcnt lgkmcnt(0)
	v_add_f32_e32 v47, v47, v52
	ds_bpermute_b32 v52, v45, v47
	s_waitcnt lgkmcnt(0)
	v_add_f32_e32 v47, v47, v52
	v_fmamk_f32 v47, v47, 0x3a800000, v33
	v_mul_f32_e32 v52, 0x4f800000, v47
	v_cmp_gt_f32_e32 vcc, s3, v47
	s_nop 1
	v_cndmask_b32_e32 v47, v47, v52, vcc
	v_sqrt_f32_e32 v52, v47
	s_nop 0
	v_add_u32_e32 v53, -1, v52
	v_add_u32_e32 v62, 1, v52
	v_fma_f32 v63, -v53, v52, v47
	v_fma_f32 v66, -v62, v52, v47
	v_cmp_ge_f32_e64 s[0:1], 0, v63
	s_nop 1
	v_cndmask_b32_e64 v52, v52, v53, s[0:1]
	v_cmp_lt_f32_e64 s[0:1], 0, v66
	s_nop 1
	v_cndmask_b32_e64 v52, v52, v62, s[0:1]
	v_mul_f32_e32 v53, 0x37800000, v52
	v_cndmask_b32_e32 v52, v52, v53, vcc
	v_cmp_class_f32_e32 vcc, v47, v46
	s_nop 1
	v_cndmask_b32_e32 v47, v52, v47, vcc
	v_div_scale_f32 v52, s[0:1], v47, v47, 1.0
	v_rcp_f32_e32 v62, v52
	v_div_scale_f32 v53, vcc, 1.0, v47, 1.0
	v_fma_f32 v63, -v52, v62, 1.0
	v_fmac_f32_e32 v62, v63, v62
	v_mul_f32_e32 v63, v53, v62
	v_fma_f32 v66, -v52, v63, v53
	v_fmac_f32_e32 v63, v66, v62
	v_fma_f32 v52, -v52, v63, v53
	v_div_fmas_f32 v52, v52, v62, v63
	v_div_fixup_f32 v52, v52, v47, 1.0
	v_pk_mul_f32 v[48:49], v[48:49], v[52:53] op_sel_hi:[1,0]
	v_pk_mul_f32 v[62:63], v[68:69], v[52:53] op_sel_hi:[1,0]
	v_pk_mul_f32 v[58:59], v[58:59], v[52:53] op_sel_hi:[1,0]
	v_pk_mul_f32 v[66:67], v[50:51], v[52:53] op_sel_hi:[1,0]
	v_pk_mul_f32 v[60:61], v[60:61], v[52:53] op_sel_hi:[1,0]
	v_pk_mul_f32 v[68:69], v[54:55], v[52:53] op_sel_hi:[1,0]
	v_pk_mul_f32 v[64:65], v[64:65], v[52:53] op_sel_hi:[1,0]
	v_pk_mul_f32 v[70:71], v[56:57], v[52:53] op_sel_hi:[1,0]
	v_pk_fma_f32 v[50:51], v[2:3], v[62:63], v[6:7]
	v_pk_fma_f32 v[48:49], v[0:1], v[48:49], v[4:5]
	v_pk_fma_f32 v[54:55], v[10:11], v[66:67], v[14:15]
	v_pk_fma_f32 v[52:53], v[8:9], v[58:59], v[12:13]
	v_pk_fma_f32 v[58:59], v[18:19], v[68:69], v[22:23]
	v_pk_fma_f32 v[56:57], v[16:17], v[60:61], v[20:21]
	v_pk_fma_f32 v[62:63], v[26:27], v[70:71], v[30:31]
	v_pk_fma_f32 v[60:61], v[24:25], v[64:65], v[28:29]
	global_store_dwordx4 v[38:39], v[48:51], off offset:-3072 nt
	global_store_dwordx4 v[38:39], v[52:55], off offset:-2048 nt
	global_store_dwordx4 v[38:39], v[56:59], off offset:-1024 nt
	global_store_dwordx4 v[38:39], v[60:63], off nt
	v_lshl_add_u64 v[38:39], v[38:39], 0, s[6:7]
	s_waitcnt vmcnt(4)
	v_mov_b32_e32 v50, v82
	v_mov_b32_e32 v51, v83
	v_mov_b32_e32 v52, v84
	v_mov_b32_e32 v53, v85
	v_mov_b32_e32 v54, v86
	v_mov_b32_e32 v55, v87
	v_mov_b32_e32 v56, v88
	v_mov_b32_e32 v57, v89
	s_andn2_b64 exec, exec, s[8:9]
	s_cbranch_execnz .LBB0_1770
